# sample-chain barrier wait: first poll of the generation word requested before the preceding store drain
# baseline (speedup 1.0000x reference)
.LBB11_392:
	v_readlane_b32 s0, v248, 20
	v_readlane_b32 s1, v248, 21
	s_add_u32 s0, s18, s0
	s_addc_u32 s1, s19, s1
	v_readlane_b32 s6, v248, 22
	v_readlane_b32 s7, v248, 23
	s_add_u32 s0, s0, s6
	v_lshlrev_b32_e32 v2, 1, v190
	s_addc_u32 s1, s1, s7
	v_ashrrev_i32_e32 v3, 31, v2
	v_lshl_add_u64 v[2:3], v[2:3], 2, s[0:1]
	v_add_co_u32_e32 v2, vcc, 0x2fb00000, v2
	s_nop 1
	v_addc_co_u32_e32 v3, vcc, 0, v3, vcc
	global_store_dwordx2 v[2:3], v[196:197], off
	s_getreg_b32 s100, hwreg(HW_REG_XCC_ID, 0, 4)
	s_and_b32 s100, s100, 15
	s_lshl_b32 s100, s100, 8
	v_readlane_b32 s101, v248, 6
	s_nop 3
	s_add_u32 s100, s101, s100
	v_readlane_b32 s101, v248, 7
	s_nop 3
	s_addc_u32 s101, s101, 0
	s_nop 4
	global_load_dword v251, v208, s[100:101] offset:1024 sc1
	s_getreg_b32 s0, hwreg(HW_REG_XCC_ID, 0, 4)
	s_waitcnt vmcnt(0)
	s_barrier
	s_mov_b64 s[6:7], exec
	v_readlane_b32 s8, v248, 2
	v_readlane_b32 s9, v248, 3
	s_and_b64 s[8:9], s[6:7], s[8:9]
	s_xor_b64 s[10:11], s[8:9], s[6:7]
	s_mov_b64 exec, s[8:9]
	s_getreg_b32 s1, hwreg(HW_REG_XCC_ID, 0, 4)
	s_andn2_saveexec_b64 s[10:11], s[10:11]
	s_cbranch_execz .LBB11_480
	v_readlane_b32 s1, v242, 31
	s_waitcnt vmcnt(0) expcnt(0) lgkmcnt(0)
	s_and_b32 s6, s0, 15
	v_mov_b32_e32 v0, s1
	ds_read_b32 v2, v0
	v_readlane_b32 s1, v242, 32
	s_waitcnt lgkmcnt(0)
	v_cmp_ne_u32_e32 vcc, 0, v2
	v_mov_b32_e32 v0, s1
	ds_read_b32 v0, v0
	s_cbranch_vccnz .LBB11_410
	s_mov_b32 s0, 1
	s_branch .LBB11_398

.LBB11_450:
	v_readlane_b32 s1, v242, 34
	s_getreg_b32 s0, hwreg(HW_REG_XCC_ID, 0, 4)
	s_and_b32 s0, s0, 15
	v_mov_b32_e32 v0, s1
	v_readlane_b32 s1, v242, 35
	ds_read_b32 v0, v0
	s_mov_b64 s[18:19], -1
	v_mov_b32_e32 v2, s1
	ds_read_b32 v2, v2
	s_waitcnt lgkmcnt(0)
	v_cmp_eq_u32_e32 vcc, 1, v2
	s_cbranch_vccnz .LBB11_465
	s_lshl_b32 s1, s0, 8
	v_readlane_b32 s6, v248, 6
	s_add_u32 s6, s6, s1
	v_readlane_b32 s1, v248, 7
	s_addc_u32 s7, s1, 0
	s_add_u32 s18, s6, 0x2400
	s_addc_u32 s19, s7, 0
	v_mov_b32_e32 v2, v251
	s_waitcnt vmcnt(0)
	v_cmp_ge_u32_e32 vcc, v2, v0
	s_cbranch_vccnz .LBB11_464
	s_mov_b32 s1, 1
	s_branch .LBB11_454

.LBB11_701:
	s_getreg_b32 s100, hwreg(HW_REG_XCC_ID, 0, 4)
	s_and_b32 s100, s100, 15
	s_lshl_b32 s100, s100, 8
	v_readlane_b32 s101, v248, 6
	s_nop 3
	s_add_u32 s100, s101, s100
	v_readlane_b32 s101, v248, 7
	s_nop 3
	s_addc_u32 s101, s101, 0
	s_nop 4
	global_load_dword v251, v208, s[100:101] offset:1024 sc1
	s_getreg_b32 s0, hwreg(HW_REG_XCC_ID, 0, 4)
	s_waitcnt vmcnt(0)
	s_barrier
	s_mov_b64 s[6:7], exec
	v_readlane_b32 s8, v248, 2
	v_readlane_b32 s9, v248, 3
	s_and_b64 s[8:9], s[6:7], s[8:9]
	s_xor_b64 s[10:11], s[8:9], s[6:7]
	s_mov_b64 exec, s[8:9]
	s_getreg_b32 s1, hwreg(HW_REG_XCC_ID, 0, 4)
	s_andn2_saveexec_b64 s[10:11], s[10:11]
	s_cbranch_execz .LBB11_789
	v_readlane_b32 s1, v242, 31
	s_waitcnt vmcnt(0) expcnt(0) lgkmcnt(0)
	s_and_b32 s6, s0, 15
	v_mov_b32_e32 v0, s1
	ds_read_b32 v2, v0
	v_readlane_b32 s1, v242, 32
	s_waitcnt lgkmcnt(0)
	v_cmp_ne_u32_e32 vcc, 0, v2
	v_mov_b32_e32 v0, s1
	ds_read_b32 v0, v0
	s_cbranch_vccnz .LBB11_719
	s_mov_b32 s0, 1
	s_branch .LBB11_707

.LBB11_759:
	v_readlane_b32 s1, v242, 34
	s_getreg_b32 s0, hwreg(HW_REG_XCC_ID, 0, 4)
	s_and_b32 s0, s0, 15
	v_mov_b32_e32 v0, s1
	v_readlane_b32 s1, v242, 35
	ds_read_b32 v0, v0
	s_mov_b64 s[12:13], -1
	v_mov_b32_e32 v2, s1
	ds_read_b32 v2, v2
	s_waitcnt lgkmcnt(0)
	v_cmp_eq_u32_e32 vcc, 1, v2
	s_cbranch_vccnz .LBB11_774
	s_lshl_b32 s1, s0, 8
	v_readlane_b32 s6, v248, 6
	s_add_u32 s6, s6, s1
	v_readlane_b32 s1, v248, 7
	s_addc_u32 s7, s1, 0
	s_add_u32 s12, s6, 0x2400
	s_addc_u32 s13, s7, 0
	v_mov_b32_e32 v2, v251
	s_waitcnt vmcnt(0)
	v_cmp_ge_u32_e32 vcc, v2, v0
	s_cbranch_vccnz .LBB11_773
	s_mov_b32 s1, 1
	s_branch .LBB11_763

.LBB11_935:
	s_getreg_b32 s100, hwreg(HW_REG_XCC_ID, 0, 4)
	s_and_b32 s100, s100, 15
	s_lshl_b32 s100, s100, 8
	v_readlane_b32 s101, v248, 6
	s_nop 3
	s_add_u32 s100, s101, s100
	v_readlane_b32 s101, v248, 7
	s_nop 3
	s_addc_u32 s101, s101, 0
	s_nop 4
	global_load_dword v251, v208, s[100:101] offset:1024 sc1
	s_getreg_b32 s0, hwreg(HW_REG_XCC_ID, 0, 4)
	s_waitcnt vmcnt(0)
	s_waitcnt lgkmcnt(0)
	s_barrier
	s_mov_b64 s[6:7], exec
	v_readlane_b32 s8, v248, 2
	v_readlane_b32 s9, v248, 3
	s_and_b64 s[8:9], s[6:7], s[8:9]
	s_xor_b64 s[10:11], s[8:9], s[6:7]
	s_mov_b64 exec, s[8:9]
	s_getreg_b32 s1, hwreg(HW_REG_XCC_ID, 0, 4)
	s_andn2_saveexec_b64 s[10:11], s[10:11]
	s_cbranch_execz .LBB11_1023
	v_readlane_b32 s1, v242, 31
	s_waitcnt vmcnt(0) expcnt(0) lgkmcnt(0)
	s_and_b32 s6, s0, 15
	v_mov_b32_e32 v0, s1
	ds_read_b32 v2, v0
	v_readlane_b32 s1, v242, 32
	s_waitcnt lgkmcnt(0)
	v_cmp_ne_u32_e32 vcc, 0, v2
	v_mov_b32_e32 v0, s1
	ds_read_b32 v0, v0
	s_cbranch_vccnz .LBB11_953
	s_mov_b32 s0, 1
	s_branch .LBB11_941

.LBB11_1215:
	s_getreg_b32 s100, hwreg(HW_REG_XCC_ID, 0, 4)
	s_and_b32 s100, s100, 15
	s_lshl_b32 s100, s100, 8
	v_readlane_b32 s101, v248, 6
	s_nop 3
	s_add_u32 s100, s101, s100
	v_readlane_b32 s101, v248, 7
	s_nop 3
	s_addc_u32 s101, s101, 0
	s_nop 4
	global_load_dword v251, v208, s[100:101] offset:1024 sc1
	s_getreg_b32 s0, hwreg(HW_REG_XCC_ID, 0, 4)
	s_waitcnt vmcnt(0)
	s_waitcnt vmcnt(0) lgkmcnt(0)
	s_barrier
	s_mov_b64 s[6:7], exec
	v_readlane_b32 s8, v248, 2
	v_readlane_b32 s9, v248, 3
	s_and_b64 s[8:9], s[6:7], s[8:9]
	s_xor_b64 s[12:13], s[8:9], s[6:7]
	s_mov_b64 exec, s[8:9]
	s_getreg_b32 s1, hwreg(HW_REG_XCC_ID, 0, 4)
	s_andn2_saveexec_b64 s[12:13], s[12:13]
	s_cbranch_execz .LBB11_1303
	v_readlane_b32 s1, v242, 31
	s_waitcnt vmcnt(0) expcnt(0) lgkmcnt(0)
	s_and_b32 s6, s0, 15
	v_mov_b32_e32 v0, s1
	ds_read_b32 v2, v0
	v_readlane_b32 s1, v242, 32
	s_waitcnt lgkmcnt(0)
	v_cmp_ne_u32_e32 vcc, 0, v2
	v_mov_b32_e32 v0, s1
	ds_read_b32 v0, v0
	s_cbranch_vccnz .LBB11_1233
	s_mov_b32 s0, 1
	s_branch .LBB11_1221

.LBB11_1273:
	v_readlane_b32 s1, v242, 34
	s_getreg_b32 s0, hwreg(HW_REG_XCC_ID, 0, 4)
	s_and_b32 s0, s0, 15
	v_mov_b32_e32 v0, s1
	v_readlane_b32 s1, v242, 35
	ds_read_b32 v0, v0
	s_mov_b64 s[14:15], -1
	v_mov_b32_e32 v2, s1
	ds_read_b32 v2, v2
	s_waitcnt lgkmcnt(0)
	v_cmp_eq_u32_e32 vcc, 1, v2
	s_cbranch_vccnz .LBB11_1288
	s_lshl_b32 s1, s0, 8
	v_readlane_b32 s6, v248, 6
	s_add_u32 s6, s6, s1
	v_readlane_b32 s1, v248, 7
	s_addc_u32 s7, s1, 0
	s_add_u32 s14, s6, 0x2400
	s_addc_u32 s15, s7, 0
	v_mov_b32_e32 v2, v251
	s_waitcnt vmcnt(0)
	v_cmp_ge_u32_e32 vcc, v2, v0
	s_cbranch_vccnz .LBB11_1287
	s_mov_b32 s1, 1
	s_branch .LBB11_1277

.LBB11_1638:
	s_getreg_b32 s100, hwreg(HW_REG_XCC_ID, 0, 4)
	s_and_b32 s100, s100, 15
	s_lshl_b32 s100, s100, 8
	v_readlane_b32 s101, v248, 6
	s_nop 3
	s_add_u32 s100, s101, s100
	v_readlane_b32 s101, v248, 7
	s_nop 3
	s_addc_u32 s101, s101, 0
	s_nop 4
	global_load_dword v251, v208, s[100:101] offset:1024 sc1
	s_getreg_b32 s0, hwreg(HW_REG_XCC_ID, 0, 4)
	s_waitcnt vmcnt(0)
	s_waitcnt lgkmcnt(0)
	s_barrier
	s_mov_b64 s[6:7], exec
	v_readlane_b32 s8, v248, 2
	v_readlane_b32 s9, v248, 3
	s_and_b64 s[8:9], s[6:7], s[8:9]
	s_xor_b64 s[10:11], s[8:9], s[6:7]
	v_readlane_b32 s58, v242, 56
	s_mov_b64 exec, s[8:9]
	s_getreg_b32 s1, hwreg(HW_REG_XCC_ID, 0, 4)
	s_andn2_saveexec_b64 s[10:11], s[10:11]
	s_cbranch_execz .LBB11_1726
	v_readlane_b32 s1, v242, 31
	s_waitcnt vmcnt(0) expcnt(0) lgkmcnt(0)
	s_and_b32 s6, s0, 15
	v_mov_b32_e32 v0, s1
	ds_read_b32 v2, v0
	v_readlane_b32 s1, v242, 32
	s_waitcnt lgkmcnt(0)
	v_cmp_ne_u32_e32 vcc, 0, v2
	v_mov_b32_e32 v0, s1
	ds_read_b32 v0, v0
	s_cbranch_vccnz .LBB11_1656
	s_mov_b32 s0, 1
	s_branch .LBB11_1644

.LBB11_2100:
	s_getreg_b32 s100, hwreg(HW_REG_XCC_ID, 0, 4)
	s_and_b32 s100, s100, 15
	s_lshl_b32 s100, s100, 8
	v_readlane_b32 s101, v248, 6
	s_nop 3
	s_add_u32 s100, s101, s100
	v_readlane_b32 s101, v248, 7
	s_nop 3
	s_addc_u32 s101, s101, 0
	s_nop 4
	global_load_dword v251, v208, s[100:101] offset:1024 sc1
	s_getreg_b32 s0, hwreg(HW_REG_XCC_ID, 0, 4)
	s_waitcnt vmcnt(0)
	s_waitcnt vmcnt(0) lgkmcnt(0)
	s_barrier
	s_mov_b64 s[6:7], exec
	v_readlane_b32 s8, v248, 2
	v_readlane_b32 s9, v248, 3
	s_and_b64 s[8:9], s[6:7], s[8:9]
	s_xor_b64 s[10:11], s[8:9], s[6:7]
	s_mov_b64 exec, s[8:9]
	s_getreg_b32 s1, hwreg(HW_REG_XCC_ID, 0, 4)
	s_andn2_saveexec_b64 s[12:13], s[10:11]
	s_cbranch_execz .LBB11_2188
	v_readlane_b32 s1, v242, 31
	s_waitcnt vmcnt(0) expcnt(0) lgkmcnt(0)
	s_and_b32 s6, s0, 15
	v_mov_b32_e32 v0, s1
	ds_read_b32 v2, v0
	v_readlane_b32 s1, v242, 32
	s_waitcnt lgkmcnt(0)
	v_cmp_ne_u32_e32 vcc, 0, v2
	v_mov_b32_e32 v0, s1
	ds_read_b32 v0, v0
	s_cbranch_vccnz .LBB11_2118
	s_mov_b32 s0, 1
	s_branch .LBB11_2106

.LBB11_2158:
	v_readlane_b32 s1, v242, 34
	s_getreg_b32 s0, hwreg(HW_REG_XCC_ID, 0, 4)
	s_and_b32 s0, s0, 15
	v_mov_b32_e32 v0, s1
	v_readlane_b32 s1, v242, 35
	ds_read_b32 v0, v0
	s_mov_b64 s[10:11], -1
	v_mov_b32_e32 v2, s1
	ds_read_b32 v2, v2
	s_waitcnt lgkmcnt(0)
	v_cmp_eq_u32_e32 vcc, 1, v2
	s_cbranch_vccnz .LBB11_2173
	s_lshl_b32 s1, s0, 8
	v_readlane_b32 s6, v248, 6
	s_add_u32 s6, s6, s1
	v_readlane_b32 s1, v248, 7
	s_addc_u32 s7, s1, 0
	s_add_u32 s10, s6, 0x2400
	s_addc_u32 s11, s7, 0
	v_mov_b32_e32 v2, v251
	s_waitcnt vmcnt(0)
	v_cmp_ge_u32_e32 vcc, v2, v0
	s_cbranch_vccnz .LBB11_2172
	s_mov_b32 s1, 1
	s_branch .LBB11_2162

.LBB11_2578:
	s_getreg_b32 s100, hwreg(HW_REG_XCC_ID, 0, 4)
	s_and_b32 s100, s100, 15
	s_lshl_b32 s100, s100, 8
	v_readlane_b32 s101, v248, 6
	s_nop 3
	s_add_u32 s100, s101, s100
	v_readlane_b32 s101, v248, 7
	s_nop 3
	s_addc_u32 s101, s101, 0
	s_nop 4
	global_load_dword v251, v208, s[100:101] offset:1024 sc1
	s_getreg_b32 s0, hwreg(HW_REG_XCC_ID, 0, 4)
	s_waitcnt vmcnt(0)
	s_waitcnt vmcnt(0) lgkmcnt(0)
	s_barrier
	s_mov_b64 s[6:7], exec
	v_readlane_b32 s8, v248, 2
	v_readlane_b32 s9, v248, 3
	s_and_b64 s[8:9], s[6:7], s[8:9]
	s_xor_b64 s[10:11], s[8:9], s[6:7]
	s_mov_b64 exec, s[8:9]
	s_getreg_b32 s1, hwreg(HW_REG_XCC_ID, 0, 4)
	s_andn2_saveexec_b64 s[10:11], s[10:11]
	s_cbranch_execz .LBB11_2666
	v_readlane_b32 s1, v242, 31
	s_waitcnt vmcnt(0) expcnt(0) lgkmcnt(0)
	s_and_b32 s6, s0, 15
	v_mov_b32_e32 v0, s1
	ds_read_b32 v2, v0
	v_readlane_b32 s1, v242, 32
	s_waitcnt lgkmcnt(0)
	v_cmp_ne_u32_e32 vcc, 0, v2
	v_mov_b32_e32 v0, s1
	ds_read_b32 v0, v0
	s_cbranch_vccnz .LBB11_2596
	s_mov_b32 s0, 1
	s_branch .LBB11_2584
